# grid barrier: XCC leader's L1 invalidate overlapped with its cross-XCC arrival atomic instead of after the release
# speedup vs baseline: 1.0258x; 1.0012x over previous
.LBB0_1208:
	s_or_b64 exec, exec, s[6:7]
	buffer_inv sc1
	s_waitcnt vmcnt(0)
	v_readfirstlane_b32 s0, v3
	v_cvt_f32_u32_e32 v3, v0
	v_sub_u32_e32 v4, 0, v0
	v_add_u32_e32 v2, s0, v2
	s_mov_b64 s[6:7], -1
	v_rcp_iflag_f32_e32 v3, v3
	s_nop 0
	v_mul_f32_e32 v3, 0x4f7ffffe, v3
	v_cvt_u32_f32_e32 v3, v3
	v_mul_lo_u32 v4, v4, v3
	v_mul_hi_u32 v4, v3, v4
	v_add_u32_e32 v3, v3, v4
	v_mul_hi_u32 v3, v2, v3
	v_mul_lo_u32 v4, v3, v0
	v_sub_u32_e32 v4, v2, v4
	v_cmp_ge_u32_e32 vcc, v4, v0
	v_add_u32_e32 v5, 1, v3
	s_nop 0
	v_cndmask_b32_e32 v3, v3, v5, vcc
	v_sub_u32_e32 v5, v4, v0
	v_cndmask_b32_e32 v4, v4, v5, vcc
	v_cmp_ge_u32_e32 vcc, v4, v0
	v_add_u32_e32 v4, 1, v3
	v_add_u32_e32 v5, 1, v2
	v_cndmask_b32_e32 v4, v3, v4, vcc
	v_mad_u64_u32 v[2:3], s[4:5], v0, v4, v[0:1]
	v_readlane_b32 s4, v254, 20
	v_readlane_b32 s5, v254, 21
	v_cmp_ne_u32_e32 vcc, v5, v2
	s_nop 0
	v_mov_b64_e32 v[2:3], s[4:5]
	s_and_saveexec_b64 s[4:5], vcc
	s_cbranch_execz .LBB0_1220
	v_readlane_b32 s6, v254, 20
	v_readlane_b32 s7, v254, 21
	s_mov_b64 s[8:9], 0
	s_nop 3
	global_load_dword v0, v1, s[6:7] sc1
	s_waitcnt vmcnt(0)
	v_cmp_eq_u32_e32 vcc, v0, v4
	s_and_saveexec_b64 s[6:7], vcc
	s_cbranch_execz .LBB0_1219
	s_mov_b32 s0, 1
	s_branch .LBB0_1212

.LBB0_1222:
	s_or_b64 exec, exec, s[4:5]
	s_mov_b64 s[4:5], exec
	v_mbcnt_lo_u32_b32 v0, s4, 0
	v_mbcnt_hi_u32_b32 v0, s5, v0
	v_cmp_eq_u32_e32 vcc, 0, v0
	s_waitcnt vmcnt(0)
	s_and_saveexec_b64 s[6:7], vcc
	s_cbranch_execnz .LBB0_1223
	s_getpc_b64 s[98:99]
